# merge odd-epilogue: first-half loads pre-issued in the last K iteration AND per-chunk counted waits (v55 + v63 combined)
# speedup vs baseline: 1.0031x; 1.0031x over previous
; DI unsigned cvtpk(float lo, float hi) { typedef float f2 __attribute__((ext_vector_type(2))); typedef __bf16 b2 __attribute__((ext_vector_type(2))); f2 v = {lo, hi}; b2 b = __builtin_convertvector(v, b2); return __builtin_bit_cast(unsigned, b); }
; DI float bflo(unsigned w) { return __uint_as_float(w << 16); }
; DI float bfhi(unsigned w) { return __uint_as_float(w & 0xffff0000u); }
;     DI void operator()(f32x4 (&acc)[2][2][4][2], const pg8::GUnit& u, int wr, int wc, int fr, int fq) const {
;         const int row0 = u.pm * 256 + wr * 64 + fr; const int col0 = u.pn * 256 + wc * 32 + 8 * fq;
;         const int z = u.z;
;         if ((z & 1) == 0) {
;     ...
;                 for (int m = 0; m < 4; ++m) { bf16_t* mp = act + (size_t)(row0 + ai * 128 + m * 16) * PITCH + C_MERGED + col0;
; #pragma unroll
;                     for (int bj = 0; bj < 2; ++bj) {
;                         const u32x4 g = gq[m][bj];
;                         const f32x4 a0 = acc[ai][bj][m][0], a1 = acc[ai][bj][m][1];
;                         float r0 = bflo(g.x) * a0[0], r1 = bfhi(g.x) * a0[1], r2 = bflo(g.y) * a0[2], r3 = bfhi(g.y) * a0[3];
;                         float r4 = bflo(g.z) * a1[0], r5 = bfhi(g.z) * a1[1], r6 = bflo(g.w) * a1[2], r7 = bfhi(g.w) * a1[3];
;                         if (z > 1) { const u32x4 pm_ = mq[m][bj];
;                             r0 += bflo(pm_.x); r1 += bfhi(pm_.x); r2 += bflo(pm_.y); r3 += bfhi(pm_.y); r4 += bflo(pm_.z); r5 += bfhi(pm_.z); r6 += bflo(pm_.w); r7 += bfhi(pm_.w); }
;                         u32x4 w; w.x = cvtpk(r0, r1); w.y = cvtpk(r2, r3); w.z = cvtpk(r4, r5); w.w = cvtpk(r6, r7);
;                         *(u32x4*)(mp + bj * 128) = w;
.LBB0_665:
	v_lshl_add_u32 v245, s57, 8, v240
	v_lshl_or_b32 v216, s56, 8, v243
	s_bitcmp0_b32 s58, 0
	s_mov_b64 s[22:23], -1
	s_cbranch_scc1 .LBB0_731
	s_cmp_gt_i32 s58, 1
	s_cselect_b64 s[44:45], 0, -1
	s_lshl_b32 s100, s31, 7
	s_add_u32 s22, s100, 0x1000
	s_mov_b32 s23, 0
	s_and_b64 vcc, exec, s[44:45]
	s_cbranch_vccnz .Lmo_h1nm_0
	s_waitcnt vmcnt(13)
	v_lshlrev_b32_e32 v218, 16, v190
	v_and_b32_e32 v219, 0xffff0000, v190
	v_lshlrev_b32_e32 v220, 16, v191
	v_and_b32_e32 v221, 0xffff0000, v191
	v_lshlrev_b32_e32 v222, 16, v192
	v_and_b32_e32 v223, 0xffff0000, v192
	v_lshlrev_b32_e32 v224, 16, v193
	v_and_b32_e32 v225, 0xffff0000, v193
	v_pk_mul_f32 v[218:219], v[126:127], v[218:219]
	v_pk_mul_f32 v[220:221], v[128:129], v[220:221]
	v_pk_mul_f32 v[222:223], v[122:123], v[222:223]
	v_pk_mul_f32 v[224:225], v[124:125], v[224:225]
	v_lshlrev_b32_e32 v190, 16, v158
	v_and_b32_e32 v191, 0xffff0000, v158
	v_pk_add_f32 v[218:219], v[218:219], v[190:191]
	v_lshlrev_b32_e32 v192, 16, v159
	v_and_b32_e32 v193, 0xffff0000, v159
	v_pk_add_f32 v[220:221], v[220:221], v[192:193]
	v_lshlrev_b32_e32 v190, 16, v160
	v_and_b32_e32 v191, 0xffff0000, v160
	v_pk_add_f32 v[222:223], v[222:223], v[190:191]
	v_lshlrev_b32_e32 v192, 16, v161
	v_and_b32_e32 v193, 0xffff0000, v161
	v_pk_add_f32 v[224:225], v[224:225], v[192:193]
	v_cvt_pk_bf16_f32 v218, v218, v219
	v_cvt_pk_bf16_f32 v219, v220, v221
	v_cvt_pk_bf16_f32 v220, v222, v223
	v_cvt_pk_bf16_f32 v221, v224, v225
	global_store_dwordx4 v[252:253], v[218:221], off offset:1024
	v_lshl_add_u64 v[190:191], v[252:253], 0, s[22:23]
	v_lshl_add_u64 v[158:159], v[252:253], 0, s[100:101]
	global_load_dwordx4 v[190:193], v[190:191], off offset:1024
	global_load_dwordx4 v[158:161], v[158:159], off offset:1024
	s_branch .Lmo_h1e_0
